# v74 + hand-scheduled RG-LRU pass-1 gate block (MFMAs of tile mt+1 ahead of tile mt's gate math, 8 independent evaluations per step, v_permlane swaps for the lane-row combines; same f32/bf16 math) + sl
# speedup vs baseline: 1.0061x; 1.0061x over previous
; #define LAS __attribute__((address_space(3)))
; __device__ __forceinline__ float bf2f(unsigned short v) { return __uint_as_float(((unsigned)v) << 16); }
; template <int PASS>
; __device__ __forceinline__ void rglru_phase(const Ctx& F, int l, const bf16_t* XRb, bf16_t* GRb, bool latent_only = false) {
;     ...
;             for (int mt = 0; mt < 4; ++mt) {
;                 f32x4 ag[4];
; #pragma unroll
;                 for (int gt = 0; gt < 4; ++gt) { const float nb = (gt & 1) ? nbx[gt >> 1] : nba[gt >> 1]; ag[gt] = (f32x4){nb, nb, nb, nb}; }
; #pragma unroll
;                 for (int ks = 0; ks < 4; ++ks) { const bf16x8 af = *(const LAS bf16x8*)(XT + (mt * 16 + l15) * XT_LD + ks * 32 + 8 * l4);
; #pragma unroll
;                     for (int gt = 0; gt < 4; ++gt) ag[gt] = __builtin_amdgcn_mfma_f32_16x16x32_bf16(af, Bf[gt][ks], ag[gt], 0, 0, 0); }
;                 float ea[2][4], eb[2][4];
; #pragma unroll
;                 for (int r = 0; r < 4; ++r) { const int tok = mt * 16 + 4 * l4 + r;
;                     const float xv = bf2f(XT[tok * XT_LD + cw + l15]);
; #pragma unroll
;                     for (int d = 0; d < 2; ++d) {
;                         const float e1 = 1.0f + __builtin_amdgcn_exp2f(ag[2 * d][r]), e2 = 1.0f + __builtin_amdgcn_exp2f(ag[2 * d + 1][r]);
;                         const float inv = __builtin_amdgcn_rcpf(e1 * e2); const float rgate = e2 * inv, igate = e1 * inv;
;                         const float a = __builtin_amdgcn_exp2f(rgate * cl2[d]);
;                         const float om = fmaf(-a, a, 1.0f);
;                         const float bv = __builtin_amdgcn_sqrtf(om) * (igate * xv);
;                         ea[d][r] = a; eb[d][r] = bv; } }
.LBB0_570:
	v_mov_b32_e32 v248, v181
	ds_read_b128 v[144:147], v178 offset:0
	ds_read_b128 v[148:151], v178 offset:64
	ds_read_b128 v[152:155], v178 offset:128
	ds_read_b128 v[200:203], v178 offset:192
	ds_read_u16 v236, v179 offset:0
	ds_read_u16 v237, v179 offset:272
	ds_read_u16 v238, v179 offset:544
	ds_read_u16 v239, v179 offset:816
	v_mov_b32_e32 v182, 1.0
	v_mov_b32_e32 v183, 0
	v_mov_b32_e32 v206, 1.0
	v_mov_b32_e32 v207, 0
	s_waitcnt lgkmcnt(4)
	v_mfma_f32_16x16x32_bf16 v[116:119], v[144:147], v[0:3], v[84:87]
	v_mfma_f32_16x16x32_bf16 v[120:123], v[144:147], v[16:19], v[88:91]
	v_mfma_f32_16x16x32_bf16 v[124:127], v[144:147], v[36:39], v[108:111]
	v_mfma_f32_16x16x32_bf16 v[128:131], v[144:147], v[52:55], v[112:115]
	v_mfma_f32_16x16x32_bf16 v[116:119], v[148:151], v[4:7], v[116:119]
	v_mfma_f32_16x16x32_bf16 v[120:123], v[148:151], v[20:23], v[120:123]
	v_mfma_f32_16x16x32_bf16 v[124:127], v[148:151], v[40:43], v[124:127]
	v_mfma_f32_16x16x32_bf16 v[128:131], v[148:151], v[56:59], v[128:131]
	v_mfma_f32_16x16x32_bf16 v[116:119], v[152:155], v[8:11], v[116:119]
	v_mfma_f32_16x16x32_bf16 v[120:123], v[152:155], v[24:27], v[120:123]
	v_mfma_f32_16x16x32_bf16 v[124:127], v[152:155], v[44:47], v[124:127]
	v_mfma_f32_16x16x32_bf16 v[128:131], v[152:155], v[60:63], v[128:131]
	v_mfma_f32_16x16x32_bf16 v[116:119], v[200:203], v[12:15], v[116:119]
	v_mfma_f32_16x16x32_bf16 v[120:123], v[200:203], v[28:31], v[120:123]
	v_mfma_f32_16x16x32_bf16 v[124:127], v[200:203], v[48:51], v[124:127]
	v_mfma_f32_16x16x32_bf16 v[128:131], v[200:203], v[64:67], v[128:131]
	ds_read_b128 v[208:211], v178 offset:4352
	ds_read_b128 v[212:215], v178 offset:4416
	ds_read_b128 v[220:223], v178 offset:4480
	ds_read_b128 v[224:227], v178 offset:4544
	ds_read_u16 v240, v179 offset:4352
	ds_read_u16 v241, v179 offset:4624
	ds_read_u16 v250, v179 offset:4896
	ds_read_u16 v251, v179 offset:5168
	s_waitcnt lgkmcnt(0)
	v_mfma_f32_16x16x32_bf16 v[184:187], v[208:211], v[0:3], v[84:87]
	v_mfma_f32_16x16x32_bf16 v[188:191], v[208:211], v[16:19], v[88:91]
	v_mfma_f32_16x16x32_bf16 v[192:195], v[208:211], v[36:39], v[108:111]
	v_mfma_f32_16x16x32_bf16 v[196:199], v[208:211], v[52:55], v[112:115]
	v_mfma_f32_16x16x32_bf16 v[184:187], v[212:215], v[4:7], v[184:187]
	v_mfma_f32_16x16x32_bf16 v[188:191], v[212:215], v[20:23], v[188:191]
	v_mfma_f32_16x16x32_bf16 v[192:195], v[212:215], v[40:43], v[192:195]
	v_mfma_f32_16x16x32_bf16 v[196:199], v[212:215], v[56:59], v[196:199]
	v_mfma_f32_16x16x32_bf16 v[184:187], v[220:223], v[8:11], v[184:187]
	v_mfma_f32_16x16x32_bf16 v[188:191], v[220:223], v[24:27], v[188:191]
	v_mfma_f32_16x16x32_bf16 v[192:195], v[220:223], v[44:47], v[192:195]
	v_mfma_f32_16x16x32_bf16 v[196:199], v[220:223], v[60:63], v[196:199]
	v_mfma_f32_16x16x32_bf16 v[184:187], v[224:227], v[12:15], v[184:187]
	v_mfma_f32_16x16x32_bf16 v[188:191], v[224:227], v[28:31], v[188:191]
	v_mfma_f32_16x16x32_bf16 v[192:195], v[224:227], v[48:51], v[192:195]
	v_mfma_f32_16x16x32_bf16 v[196:199], v[224:227], v[64:67], v[196:199]
	ds_read_b128 v[144:147], v178 offset:8704
	ds_read_b128 v[148:151], v178 offset:8768
	ds_read_b128 v[152:155], v178 offset:8832
	ds_read_b128 v[200:203], v178 offset:8896
	s_nop 7
	v_lshlrev_b32_e32 v236, 16, v236
	v_lshlrev_b32_e32 v237, 16, v237
	v_lshlrev_b32_e32 v238, 16, v238
	v_lshlrev_b32_e32 v239, 16, v239
	v_exp_f32_e32 v116, v116
	v_exp_f32_e32 v118, v118
	v_exp_f32_e32 v124, v124
	v_exp_f32_e32 v126, v126
	v_exp_f32_e32 v117, v117
	v_exp_f32_e32 v119, v119
	v_exp_f32_e32 v125, v125
	v_pk_add_f32 v[116:117], v[116:117], 1.0 op_sel_hi:[1,0]
	v_pk_add_f32 v[118:119], v[118:119], 1.0 op_sel_hi:[1,0]
	v_exp_f32_e32 v128, v128
	v_pk_add_f32 v[124:125], v[124:125], 1.0 op_sel_hi:[1,0]
	v_exp_f32_e32 v127, v127
	v_exp_f32_e32 v120, v120
	v_exp_f32_e32 v122, v122
	v_pk_add_f32 v[126:127], v[126:127], 1.0 op_sel_hi:[1,0]
	v_exp_f32_e32 v121, v121
	v_exp_f32_e32 v123, v123
	v_exp_f32_e32 v129, v129
	v_exp_f32_e32 v130, v130
	v_pk_add_f32 v[120:121], v[120:121], 1.0 op_sel_hi:[1,0]
	v_pk_add_f32 v[122:123], v[122:123], 1.0 op_sel_hi:[1,0]
	v_exp_f32_e32 v131, v131
	v_pk_mul_f32 v[228:229], v[116:117], v[120:121]
	v_pk_mul_f32 v[230:231], v[118:119], v[122:123]
	v_pk_add_f32 v[128:129], v[128:129], 1.0 op_sel_hi:[1,0]
	v_pk_add_f32 v[130:131], v[130:131], 1.0 op_sel_hi:[1,0]
	v_rcp_f32_e32 v228, v228
	v_rcp_f32_e32 v230, v230
	v_pk_mul_f32 v[232:233], v[124:125], v[128:129]
	v_pk_mul_f32 v[234:235], v[126:127], v[130:131]
	v_rcp_f32_e32 v229, v229
	v_rcp_f32_e32 v231, v231
	v_rcp_f32_e32 v232, v232
	v_rcp_f32_e32 v234, v234
	v_pk_mul_f32 v[120:121], v[120:121], v[228:229]
	v_pk_mul_f32 v[122:123], v[122:123], v[230:231]
	v_rcp_f32_e32 v233, v233
	v_pk_mul_f32 v[120:121], v[120:121], v[180:181] op_sel_hi:[1,0]
	v_pk_mul_f32 v[122:123], v[122:123], v[180:181] op_sel_hi:[1,0]
	v_rcp_f32_e32 v235, v235
	v_pk_mul_f32 v[116:117], v[116:117], v[228:229]
	v_pk_mul_f32 v[118:119], v[118:119], v[230:231]
	v_exp_f32_e32 v120, v120
	v_pk_mul_f32 v[128:129], v[128:129], v[232:233]
	v_pk_mul_f32 v[130:131], v[130:131], v[234:235]
	v_exp_f32_e32 v121, v121
	v_pk_mul_f32 v[118:119], v[118:119], v[238:239]
	v_pk_mul_f32 v[128:129], v[128:129], v[248:249] op_sel_hi:[1,0]
	v_exp_f32_e32 v122, v122
	v_pk_mul_f32 v[124:125], v[124:125], v[232:233]
	v_pk_mul_f32 v[130:131], v[130:131], v[248:249] op_sel_hi:[1,0]
	v_exp_f32_e32 v123, v123
	v_pk_mul_f32 v[124:125], v[124:125], v[236:237]
	v_pk_mul_f32 v[126:127], v[126:127], v[234:235]
	v_exp_f32_e32 v128, v128
	v_pk_mul_f32 v[116:117], v[116:117], v[236:237]
	v_pk_fma_f32 v[230:231], v[122:123], v[122:123], 1.0 op_sel_hi:[1,1,0] neg_lo:[1,0,0] neg_hi:[1,0,0]
; template <int PASS>
; __device__ __forceinline__ void rglru_phase(const Ctx& F, int l, const bf16_t* XRb, bf16_t* GRb, bool latent_only = false) {
;     ...
;                 for (int r = 0; r < 4; ++r) { const int tok = mt * 16 + 4 * l4 + r;
;                     const float xv = bf2f(XT[tok * XT_LD + cw + l15]);
; #pragma unroll
;                     for (int d = 0; d < 2; ++d) {
;                         const float e1 = 1.0f + __builtin_amdgcn_exp2f(ag[2 * d][r]), e2 = 1.0f + __builtin_amdgcn_exp2f(ag[2 * d + 1][r]);
;                         const float inv = __builtin_amdgcn_rcpf(e1 * e2); const float rgate = e2 * inv, igate = e1 * inv;
;                         const float a = __builtin_amdgcn_exp2f(rgate * cl2[d]);
;                         const float om = fmaf(-a, a, 1.0f);
;                         const float bv = __builtin_amdgcn_sqrtf(om) * (igate * xv);
;                         ea[d][r] = a; eb[d][r] = bv; } }
;                 if (PASS == 1) {
; #pragma unroll
;                     for (int d = 0; d < 2; ++d) {
;                         float A, B;
;                         if (d == 0) { A = ea[0][0]; B = eb[0][0];
; #pragma unroll
;                             for (int r = 1; r < 4; ++r) { B = ea[0][r] * B + eb[0][r]; A *= ea[0][r]; } }
;                         else { A = ea[1][3]; B = eb[1][3];
; #pragma unroll
;                             for (int r = 2; r >= 0; --r) { B = ea[1][r] * B + eb[1][r]; A *= ea[1][r]; } }
;                         { const float Ap = __uint_as_float(__builtin_amdgcn_ds_bpermute((lane ^ 16) << 2, __float_as_uint(A))), Bp = __uint_as_float(__builtin_amdgcn_ds_bpermute((lane ^ 16) << 2, __float_as_uint(B)));
;                           const bool mefirst = d == 0 ? ((l4 & 1) == 0) : ((l4 & 1) == 1);
;                           const float nB = mefirst ? Ap * B + Bp : A * Bp + B; A = A * Ap; B = nB; }
;                         { const float Ap = __uint_as_float(__builtin_amdgcn_ds_bpermute((lane ^ 32) << 2, __float_as_uint(A))), Bp = __uint_as_float(__builtin_amdgcn_ds_bpermute((lane ^ 32) << 2, __float_as_uint(B)));
;                           const bool mefirst = d == 0 ? (l4 < 2) : (l4 >= 2);
;                           const float nB = mefirst ? Ap * B + Bp : A * Bp + B; A = A * Ap; B = nB; }
;                         if (d == 0) { aggB[0] = A * aggB[0] + B; aggA[0] *= A; }
	v_exp_f32_e32 v129, v129
	v_pk_mul_f32 v[126:127], v[126:127], v[238:239]
	v_pk_fma_f32 v[228:229], v[120:121], v[120:121], 1.0 op_sel_hi:[1,1,0] neg_lo:[1,0,0] neg_hi:[1,0,0]
	v_sqrt_f32_e32 v230, v230
	v_pk_fma_f32 v[232:233], v[128:129], v[128:129], 1.0 op_sel_hi:[1,1,0] neg_lo:[1,0,0] neg_hi:[1,0,0]
	v_exp_f32_e32 v130, v130
	v_sqrt_f32_e32 v228, v228
	v_sqrt_f32_e32 v231, v231
	v_sqrt_f32_e32 v232, v232
	v_exp_f32_e32 v131, v131
	v_pk_mul_f32 v[118:119], v[230:231], v[118:119]
	v_sqrt_f32_e32 v233, v233
	v_sqrt_f32_e32 v229, v229
	v_pk_fma_f32 v[234:235], v[130:131], v[130:131], 1.0 op_sel_hi:[1,1,0] neg_lo:[1,0,0] neg_hi:[1,0,0]
	v_pk_mul_f32 v[124:125], v[232:233], v[124:125]
	v_pk_mul_f32 v[116:117], v[228:229], v[116:117]
	v_sqrt_f32_e32 v234, v234
	v_sqrt_f32_e32 v235, v235
	s_nop 0
	s_nop 0
	v_pk_mul_f32 v[126:127], v[234:235], v[126:127]
	ds_read_u16 v236, v179 offset:8704
	ds_read_u16 v237, v179 offset:8976
	ds_read_u16 v238, v179 offset:9248
	ds_read_u16 v239, v179 offset:9520
	v_mov_b32_e32 v161, v116
	v_mov_b32_e32 v163, v127
	v_mov_b32_e32 v160, v120
	v_mov_b32_e32 v162, v131
	v_fma_f32 v161, v121, v161, v117
	v_fma_f32 v163, v130, v163, v126
	v_mul_f32_e32 v160, v160, v121
	v_mul_f32_e32 v162, v162, v130
	v_fma_f32 v161, v122, v161, v118
	v_fma_f32 v163, v129, v163, v125
	v_mul_f32_e32 v160, v160, v122
	v_mul_f32_e32 v162, v162, v129
	v_fma_f32 v161, v123, v161, v119
	v_fma_f32 v163, v128, v163, v124
	v_mul_f32_e32 v160, v160, v123
	v_mul_f32_e32 v162, v162, v128
	v_mov_b32_e32 v164, v160
	v_mov_b32_e32 v165, v161
	v_mov_b32_e32 v156, v162
	v_mov_b32_e32 v157, v163
	v_permlane16_swap_b32_e32 v160, v164
	v_permlane16_swap_b32_e32 v161, v165
	v_permlane16_swap_b32_e32 v162, v156
	v_permlane16_swap_b32_e32 v163, v157
	v_fma_f32 v161, v164, v161, v165
	v_fma_f32 v163, v162, v157, v163
	v_mul_f32_e32 v160, v160, v164
	v_mul_f32_e32 v162, v162, v156
	v_mov_b32_e32 v164, v160
	v_mov_b32_e32 v165, v161
	v_mov_b32_e32 v156, v162
	v_mov_b32_e32 v157, v163
	v_permlane32_swap_b32_e32 v160, v164
	v_permlane32_swap_b32_e32 v161, v165
	v_permlane32_swap_b32_e32 v162, v156
	v_permlane32_swap_b32_e32 v163, v157
	v_fma_f32 v161, v164, v161, v165
	v_fma_f32 v163, v162, v157, v163
	v_mul_f32_e32 v160, v160, v164
	v_mul_f32_e32 v162, v162, v156
	v_fma_f32 v183, v160, v183, v161
	v_fma_f32 v207, v206, v163, v207
	v_mul_f32_e32 v182, v182, v160
	v_mul_f32_e32 v206, v206, v162
	s_waitcnt lgkmcnt(0)
	v_mfma_f32_16x16x32_bf16 v[116:119], v[144:147], v[0:3], v[84:87]
	v_mfma_f32_16x16x32_bf16 v[120:123], v[144:147], v[16:19], v[88:91]
	v_mfma_f32_16x16x32_bf16 v[124:127], v[144:147], v[36:39], v[108:111]
	v_mfma_f32_16x16x32_bf16 v[128:131], v[144:147], v[52:55], v[112:115]
	v_mfma_f32_16x16x32_bf16 v[116:119], v[148:151], v[4:7], v[116:119]
	v_mfma_f32_16x16x32_bf16 v[120:123], v[148:151], v[20:23], v[120:123]
	v_mfma_f32_16x16x32_bf16 v[124:127], v[148:151], v[40:43], v[124:127]
	v_mfma_f32_16x16x32_bf16 v[128:131], v[148:151], v[56:59], v[128:131]
	v_mfma_f32_16x16x32_bf16 v[116:119], v[152:155], v[8:11], v[116:119]
	v_mfma_f32_16x16x32_bf16 v[120:123], v[152:155], v[24:27], v[120:123]
	v_mfma_f32_16x16x32_bf16 v[124:127], v[152:155], v[44:47], v[124:127]
	v_mfma_f32_16x16x32_bf16 v[128:131], v[152:155], v[60:63], v[128:131]
	v_mfma_f32_16x16x32_bf16 v[116:119], v[200:203], v[12:15], v[116:119]
	v_mfma_f32_16x16x32_bf16 v[120:123], v[200:203], v[28:31], v[120:123]
	v_mfma_f32_16x16x32_bf16 v[124:127], v[200:203], v[48:51], v[124:127]
	v_mfma_f32_16x16x32_bf16 v[128:131], v[200:203], v[64:67], v[128:131]
	ds_read_b128 v[208:211], v178 offset:13056
	ds_read_b128 v[212:215], v178 offset:13120
	ds_read_b128 v[220:223], v178 offset:13184
	ds_read_b128 v[224:227], v178 offset:13248
	v_lshlrev_b32_e32 v240, 16, v240
	v_lshlrev_b32_e32 v241, 16, v241
	v_lshlrev_b32_e32 v250, 16, v250
	v_lshlrev_b32_e32 v251, 16, v251
	v_exp_f32_e32 v184, v184
	v_exp_f32_e32 v186, v186
	v_exp_f32_e32 v192, v192
	v_exp_f32_e32 v194, v194
	v_exp_f32_e32 v185, v185
	v_exp_f32_e32 v187, v187
	v_exp_f32_e32 v193, v193
	v_pk_add_f32 v[184:185], v[184:185], 1.0 op_sel_hi:[1,0]
	v_pk_add_f32 v[186:187], v[186:187], 1.0 op_sel_hi:[1,0]
	v_exp_f32_e32 v196, v196
	v_pk_add_f32 v[192:193], v[192:193], 1.0 op_sel_hi:[1,0]
	v_exp_f32_e32 v195, v195
	v_exp_f32_e32 v188, v188
	v_exp_f32_e32 v190, v190
	v_pk_add_f32 v[194:195], v[194:195], 1.0 op_sel_hi:[1,0]
	v_exp_f32_e32 v189, v189
	v_exp_f32_e32 v191, v191
	v_exp_f32_e32 v197, v197
	v_exp_f32_e32 v198, v198
	v_pk_add_f32 v[188:189], v[188:189], 1.0 op_sel_hi:[1,0]
	v_pk_add_f32 v[190:191], v[190:191], 1.0 op_sel_hi:[1,0]
	v_exp_f32_e32 v199, v199
	v_pk_mul_f32 v[228:229], v[184:185], v[188:189]
	v_pk_mul_f32 v[230:231], v[186:187], v[190:191]
	v_pk_add_f32 v[196:197], v[196:197], 1.0 op_sel_hi:[1,0]
	v_pk_add_f32 v[198:199], v[198:199], 1.0 op_sel_hi:[1,0]
	v_rcp_f32_e32 v228, v228
	v_rcp_f32_e32 v230, v230
	v_pk_mul_f32 v[232:233], v[192:193], v[196:197]
	v_pk_mul_f32 v[234:235], v[194:195], v[198:199]
	v_rcp_f32_e32 v229, v229
	v_rcp_f32_e32 v231, v231
	v_rcp_f32_e32 v232, v232
	v_rcp_f32_e32 v234, v234
	v_pk_mul_f32 v[188:189], v[188:189], v[228:229]
	v_pk_mul_f32 v[190:191], v[190:191], v[230:231]
	v_rcp_f32_e32 v233, v233
	v_pk_mul_f32 v[188:189], v[188:189], v[180:181] op_sel_hi:[1,0]
	v_pk_mul_f32 v[190:191], v[190:191], v[180:181] op_sel_hi:[1,0]
	v_rcp_f32_e32 v235, v235
	v_pk_mul_f32 v[184:185], v[184:185], v[228:229]
	v_pk_mul_f32 v[186:187], v[186:187], v[230:231]
	v_exp_f32_e32 v188, v188
	v_pk_mul_f32 v[196:197], v[196:197], v[232:233]
	v_pk_mul_f32 v[198:199], v[198:199], v[234:235]
	v_exp_f32_e32 v189, v189
; template <int PASS>
; __device__ __forceinline__ void rglru_phase(const Ctx& F, int l, const bf16_t* XRb, bf16_t* GRb, bool latent_only = false) {
;     ...
;                 for (int r = 0; r < 4; ++r) { const int tok = mt * 16 + 4 * l4 + r;
;                     const float xv = bf2f(XT[tok * XT_LD + cw + l15]);
; #pragma unroll
;                     for (int d = 0; d < 2; ++d) {
;                         const float e1 = 1.0f + __builtin_amdgcn_exp2f(ag[2 * d][r]), e2 = 1.0f + __builtin_amdgcn_exp2f(ag[2 * d + 1][r]);
;                         const float inv = __builtin_amdgcn_rcpf(e1 * e2); const float rgate = e2 * inv, igate = e1 * inv;
;                         const float a = __builtin_amdgcn_exp2f(rgate * cl2[d]);
;                         const float om = fmaf(-a, a, 1.0f);
;                         const float bv = __builtin_amdgcn_sqrtf(om) * (igate * xv);
;                         ea[d][r] = a; eb[d][r] = bv; } }
;                 if (PASS == 1) {
; #pragma unroll
;                     for (int d = 0; d < 2; ++d) {
;                         float A, B;
;                         if (d == 0) { A = ea[0][0]; B = eb[0][0];
; #pragma unroll
;                             for (int r = 1; r < 4; ++r) { B = ea[0][r] * B + eb[0][r]; A *= ea[0][r]; } }
;                         else { A = ea[1][3]; B = eb[1][3];
; #pragma unroll
;                             for (int r = 2; r >= 0; --r) { B = ea[1][r] * B + eb[1][r]; A *= ea[1][r]; } }
;                         { const float Ap = __uint_as_float(__builtin_amdgcn_ds_bpermute((lane ^ 16) << 2, __float_as_uint(A))), Bp = __uint_as_float(__builtin_amdgcn_ds_bpermute((lane ^ 16) << 2, __float_as_uint(B)));
;                           const bool mefirst = d == 0 ? ((l4 & 1) == 0) : ((l4 & 1) == 1);
;                           const float nB = mefirst ? Ap * B + Bp : A * Bp + B; A = A * Ap; B = nB; }
;                         { const float Ap = __uint_as_float(__builtin_amdgcn_ds_bpermute((lane ^ 32) << 2, __float_as_uint(A))), Bp = __uint_as_float(__builtin_amdgcn_ds_bpermute((lane ^ 32) << 2, __float_as_uint(B)));
;                           const bool mefirst = d == 0 ? (l4 < 2) : (l4 >= 2);
;                           const float nB = mefirst ? Ap * B + Bp : A * Bp + B; A = A * Ap; B = nB; }
;                         if (d == 0) { aggB[0] = A * aggB[0] + B; aggA[0] *= A; }
	v_pk_mul_f32 v[186:187], v[186:187], v[250:251]
	v_pk_mul_f32 v[196:197], v[196:197], v[248:249] op_sel_hi:[1,0]
	v_exp_f32_e32 v190, v190
	v_pk_mul_f32 v[192:193], v[192:193], v[232:233]
	v_pk_mul_f32 v[198:199], v[198:199], v[248:249] op_sel_hi:[1,0]
	v_exp_f32_e32 v191, v191
	v_pk_mul_f32 v[192:193], v[192:193], v[240:241]
	v_pk_mul_f32 v[194:195], v[194:195], v[234:235]
	v_exp_f32_e32 v196, v196
	v_pk_mul_f32 v[184:185], v[184:185], v[240:241]
	v_pk_fma_f32 v[230:231], v[190:191], v[190:191], 1.0 op_sel_hi:[1,1,0] neg_lo:[1,0,0] neg_hi:[1,0,0]
	v_exp_f32_e32 v197, v197
	v_pk_mul_f32 v[194:195], v[194:195], v[250:251]
	v_pk_fma_f32 v[228:229], v[188:189], v[188:189], 1.0 op_sel_hi:[1,1,0] neg_lo:[1,0,0] neg_hi:[1,0,0]
	v_sqrt_f32_e32 v230, v230
	v_pk_fma_f32 v[232:233], v[196:197], v[196:197], 1.0 op_sel_hi:[1,1,0] neg_lo:[1,0,0] neg_hi:[1,0,0]
	v_exp_f32_e32 v198, v198
	v_sqrt_f32_e32 v228, v228
	v_sqrt_f32_e32 v231, v231
	v_sqrt_f32_e32 v232, v232
	v_exp_f32_e32 v199, v199
	v_pk_mul_f32 v[186:187], v[230:231], v[186:187]
	v_sqrt_f32_e32 v233, v233
	v_sqrt_f32_e32 v229, v229
	v_pk_fma_f32 v[234:235], v[198:199], v[198:199], 1.0 op_sel_hi:[1,1,0] neg_lo:[1,0,0] neg_hi:[1,0,0]
	v_pk_mul_f32 v[192:193], v[232:233], v[192:193]
	v_pk_mul_f32 v[184:185], v[228:229], v[184:185]
	v_sqrt_f32_e32 v234, v234
	v_sqrt_f32_e32 v235, v235
	s_nop 0
	s_nop 0
	v_pk_mul_f32 v[194:195], v[234:235], v[194:195]
	ds_read_u16 v240, v179 offset:13056
	ds_read_u16 v241, v179 offset:13328
	ds_read_u16 v250, v179 offset:13600
	ds_read_u16 v251, v179 offset:13872
	v_mov_b32_e32 v161, v184
	v_mov_b32_e32 v163, v195
	v_mov_b32_e32 v160, v188
	v_mov_b32_e32 v162, v199
	v_fma_f32 v161, v189, v161, v185
	v_fma_f32 v163, v198, v163, v194
	v_mul_f32_e32 v160, v160, v189
	v_mul_f32_e32 v162, v162, v198
	v_fma_f32 v161, v190, v161, v186
	v_fma_f32 v163, v197, v163, v193
	v_mul_f32_e32 v160, v160, v190
	v_mul_f32_e32 v162, v162, v197
	v_fma_f32 v161, v191, v161, v187
	v_fma_f32 v163, v196, v163, v192
	v_mul_f32_e32 v160, v160, v191
	v_mul_f32_e32 v162, v162, v196
	v_mov_b32_e32 v164, v160
	v_mov_b32_e32 v165, v161
	v_mov_b32_e32 v156, v162
	v_mov_b32_e32 v157, v163
	v_permlane16_swap_b32_e32 v160, v164
	v_permlane16_swap_b32_e32 v161, v165
	v_permlane16_swap_b32_e32 v162, v156
	v_permlane16_swap_b32_e32 v163, v157
	v_fma_f32 v161, v164, v161, v165
	v_fma_f32 v163, v162, v157, v163
	v_mul_f32_e32 v160, v160, v164
	v_mul_f32_e32 v162, v162, v156
	v_mov_b32_e32 v164, v160
	v_mov_b32_e32 v165, v161
	v_mov_b32_e32 v156, v162
	v_mov_b32_e32 v157, v163
	v_permlane32_swap_b32_e32 v160, v164
	v_permlane32_swap_b32_e32 v161, v165
	v_permlane32_swap_b32_e32 v162, v156
	v_permlane32_swap_b32_e32 v163, v157
	v_fma_f32 v161, v164, v161, v165
	v_fma_f32 v163, v162, v157, v163
	v_mul_f32_e32 v160, v160, v164
	v_mul_f32_e32 v162, v162, v156
	v_fma_f32 v183, v160, v183, v161
	v_fma_f32 v207, v206, v163, v207
	v_mul_f32_e32 v182, v182, v160
	v_mul_f32_e32 v206, v206, v162
	s_waitcnt lgkmcnt(0)
	v_mfma_f32_16x16x32_bf16 v[184:187], v[208:211], v[0:3], v[84:87]
	v_mfma_f32_16x16x32_bf16 v[188:191], v[208:211], v[16:19], v[88:91]
	v_mfma_f32_16x16x32_bf16 v[192:195], v[208:211], v[36:39], v[108:111]
	v_mfma_f32_16x16x32_bf16 v[196:199], v[208:211], v[52:55], v[112:115]
	v_mfma_f32_16x16x32_bf16 v[184:187], v[212:215], v[4:7], v[184:187]
	v_mfma_f32_16x16x32_bf16 v[188:191], v[212:215], v[20:23], v[188:191]
	v_mfma_f32_16x16x32_bf16 v[192:195], v[212:215], v[40:43], v[192:195]
	v_mfma_f32_16x16x32_bf16 v[196:199], v[212:215], v[56:59], v[196:199]
	v_mfma_f32_16x16x32_bf16 v[184:187], v[220:223], v[8:11], v[184:187]
	v_mfma_f32_16x16x32_bf16 v[188:191], v[220:223], v[24:27], v[188:191]
	v_mfma_f32_16x16x32_bf16 v[192:195], v[220:223], v[44:47], v[192:195]
	v_mfma_f32_16x16x32_bf16 v[196:199], v[220:223], v[60:63], v[196:199]
	v_mfma_f32_16x16x32_bf16 v[184:187], v[224:227], v[12:15], v[184:187]
	v_mfma_f32_16x16x32_bf16 v[188:191], v[224:227], v[28:31], v[188:191]
	v_mfma_f32_16x16x32_bf16 v[192:195], v[224:227], v[48:51], v[192:195]
	v_mfma_f32_16x16x32_bf16 v[196:199], v[224:227], v[64:67], v[196:199]
	v_lshlrev_b32_e32 v236, 16, v236
	v_lshlrev_b32_e32 v237, 16, v237
	v_lshlrev_b32_e32 v238, 16, v238
	v_lshlrev_b32_e32 v239, 16, v239
	v_exp_f32_e32 v116, v116
	v_exp_f32_e32 v118, v118
	v_exp_f32_e32 v124, v124
	v_exp_f32_e32 v126, v126
	v_exp_f32_e32 v117, v117
	v_exp_f32_e32 v119, v119
	v_exp_f32_e32 v125, v125
	v_pk_add_f32 v[116:117], v[116:117], 1.0 op_sel_hi:[1,0]
	v_pk_add_f32 v[118:119], v[118:119], 1.0 op_sel_hi:[1,0]
	v_exp_f32_e32 v128, v128
	v_pk_add_f32 v[124:125], v[124:125], 1.0 op_sel_hi:[1,0]
	v_exp_f32_e32 v127, v127
	v_exp_f32_e32 v120, v120
	v_exp_f32_e32 v122, v122
	v_pk_add_f32 v[126:127], v[126:127], 1.0 op_sel_hi:[1,0]
	v_exp_f32_e32 v121, v121
	v_exp_f32_e32 v123, v123
	v_exp_f32_e32 v129, v129
	v_exp_f32_e32 v130, v130
	v_pk_add_f32 v[120:121], v[120:121], 1.0 op_sel_hi:[1,0]
	v_pk_add_f32 v[122:123], v[122:123], 1.0 op_sel_hi:[1,0]
	v_exp_f32_e32 v131, v131
	v_pk_mul_f32 v[228:229], v[116:117], v[120:121]
	v_pk_mul_f32 v[230:231], v[118:119], v[122:123]
	v_pk_add_f32 v[128:129], v[128:129], 1.0 op_sel_hi:[1,0]
	v_pk_add_f32 v[130:131], v[130:131], 1.0 op_sel_hi:[1,0]
	v_rcp_f32_e32 v228, v228
	v_rcp_f32_e32 v230, v230
	v_pk_mul_f32 v[232:233], v[124:125], v[128:129]
	v_pk_mul_f32 v[234:235], v[126:127], v[130:131]
	v_rcp_f32_e32 v229, v229
	v_rcp_f32_e32 v231, v231
	v_rcp_f32_e32 v232, v232
	v_rcp_f32_e32 v234, v234
	v_pk_mul_f32 v[120:121], v[120:121], v[228:229]
	v_pk_mul_f32 v[122:123], v[122:123], v[230:231]
	v_rcp_f32_e32 v233, v233
; template <int PASS>
; __device__ __forceinline__ void rglru_phase(const Ctx& F, int l, const bf16_t* XRb, bf16_t* GRb, bool latent_only = false) {
;     ...
;                 for (int r = 0; r < 4; ++r) { const int tok = mt * 16 + 4 * l4 + r;
;                     const float xv = bf2f(XT[tok * XT_LD + cw + l15]);
; #pragma unroll
;                     for (int d = 0; d < 2; ++d) {
;                         const float e1 = 1.0f + __builtin_amdgcn_exp2f(ag[2 * d][r]), e2 = 1.0f + __builtin_amdgcn_exp2f(ag[2 * d + 1][r]);
;                         const float inv = __builtin_amdgcn_rcpf(e1 * e2); const float rgate = e2 * inv, igate = e1 * inv;
;                         const float a = __builtin_amdgcn_exp2f(rgate * cl2[d]);
;                         const float om = fmaf(-a, a, 1.0f);
;                         const float bv = __builtin_amdgcn_sqrtf(om) * (igate * xv);
;                         ea[d][r] = a; eb[d][r] = bv; } }
;                 if (PASS == 1) {
; #pragma unroll
;                     for (int d = 0; d < 2; ++d) {
;                         float A, B;
;                         if (d == 0) { A = ea[0][0]; B = eb[0][0];
; #pragma unroll
;                             for (int r = 1; r < 4; ++r) { B = ea[0][r] * B + eb[0][r]; A *= ea[0][r]; } }
;                         else { A = ea[1][3]; B = eb[1][3];
; #pragma unroll
;                             for (int r = 2; r >= 0; --r) { B = ea[1][r] * B + eb[1][r]; A *= ea[1][r]; } }
;                         { const float Ap = __uint_as_float(__builtin_amdgcn_ds_bpermute((lane ^ 16) << 2, __float_as_uint(A))), Bp = __uint_as_float(__builtin_amdgcn_ds_bpermute((lane ^ 16) << 2, __float_as_uint(B)));
;                           const bool mefirst = d == 0 ? ((l4 & 1) == 0) : ((l4 & 1) == 1);
;                           const float nB = mefirst ? Ap * B + Bp : A * Bp + B; A = A * Ap; B = nB; }
;                         { const float Ap = __uint_as_float(__builtin_amdgcn_ds_bpermute((lane ^ 32) << 2, __float_as_uint(A))), Bp = __uint_as_float(__builtin_amdgcn_ds_bpermute((lane ^ 32) << 2, __float_as_uint(B)));
;                           const bool mefirst = d == 0 ? (l4 < 2) : (l4 >= 2);
;                           const float nB = mefirst ? Ap * B + Bp : A * Bp + B; A = A * Ap; B = nB; }
;                         if (d == 0) { aggB[0] = A * aggB[0] + B; aggA[0] *= A; }
	v_pk_mul_f32 v[120:121], v[120:121], v[180:181] op_sel_hi:[1,0]
	v_pk_mul_f32 v[122:123], v[122:123], v[180:181] op_sel_hi:[1,0]
	v_rcp_f32_e32 v235, v235
	v_pk_mul_f32 v[116:117], v[116:117], v[228:229]
	v_pk_mul_f32 v[118:119], v[118:119], v[230:231]
	v_exp_f32_e32 v120, v120
	v_pk_mul_f32 v[128:129], v[128:129], v[232:233]
	v_pk_mul_f32 v[130:131], v[130:131], v[234:235]
	v_exp_f32_e32 v121, v121
	v_pk_mul_f32 v[118:119], v[118:119], v[238:239]
	v_pk_mul_f32 v[128:129], v[128:129], v[248:249] op_sel_hi:[1,0]
	v_exp_f32_e32 v122, v122
	v_pk_mul_f32 v[124:125], v[124:125], v[232:233]
	v_pk_mul_f32 v[130:131], v[130:131], v[248:249] op_sel_hi:[1,0]
	v_exp_f32_e32 v123, v123
	v_pk_mul_f32 v[124:125], v[124:125], v[236:237]
	v_pk_mul_f32 v[126:127], v[126:127], v[234:235]
	v_exp_f32_e32 v128, v128
	v_pk_mul_f32 v[116:117], v[116:117], v[236:237]
	v_pk_fma_f32 v[230:231], v[122:123], v[122:123], 1.0 op_sel_hi:[1,1,0] neg_lo:[1,0,0] neg_hi:[1,0,0]
	v_exp_f32_e32 v129, v129
	v_pk_mul_f32 v[126:127], v[126:127], v[238:239]
	v_pk_fma_f32 v[228:229], v[120:121], v[120:121], 1.0 op_sel_hi:[1,1,0] neg_lo:[1,0,0] neg_hi:[1,0,0]
	v_sqrt_f32_e32 v230, v230
	v_pk_fma_f32 v[232:233], v[128:129], v[128:129], 1.0 op_sel_hi:[1,1,0] neg_lo:[1,0,0] neg_hi:[1,0,0]
	v_exp_f32_e32 v130, v130
	v_sqrt_f32_e32 v228, v228
	v_sqrt_f32_e32 v231, v231
	v_sqrt_f32_e32 v232, v232
	v_exp_f32_e32 v131, v131
	v_pk_mul_f32 v[118:119], v[230:231], v[118:119]
	v_sqrt_f32_e32 v233, v233
	v_sqrt_f32_e32 v229, v229
	v_pk_fma_f32 v[234:235], v[130:131], v[130:131], 1.0 op_sel_hi:[1,1,0] neg_lo:[1,0,0] neg_hi:[1,0,0]
	v_pk_mul_f32 v[124:125], v[232:233], v[124:125]
	v_pk_mul_f32 v[116:117], v[228:229], v[116:117]
	v_sqrt_f32_e32 v234, v234
	v_sqrt_f32_e32 v235, v235
	s_nop 0
	s_nop 0
	v_pk_mul_f32 v[126:127], v[234:235], v[126:127]
	v_mov_b32_e32 v161, v116
	v_mov_b32_e32 v163, v127
	v_mov_b32_e32 v160, v120
	v_mov_b32_e32 v162, v131
	v_fma_f32 v161, v121, v161, v117
	v_fma_f32 v163, v130, v163, v126
	v_mul_f32_e32 v160, v160, v121
	v_mul_f32_e32 v162, v162, v130
	v_fma_f32 v161, v122, v161, v118
	v_fma_f32 v163, v129, v163, v125
	v_mul_f32_e32 v160, v160, v122
	v_mul_f32_e32 v162, v162, v129
	v_fma_f32 v161, v123, v161, v119
	v_fma_f32 v163, v128, v163, v124
	v_mul_f32_e32 v160, v160, v123
	v_mul_f32_e32 v162, v162, v128
	v_mov_b32_e32 v164, v160
	v_mov_b32_e32 v165, v161
	v_mov_b32_e32 v156, v162
	v_mov_b32_e32 v157, v163
	v_permlane16_swap_b32_e32 v160, v164
	v_permlane16_swap_b32_e32 v161, v165
	v_permlane16_swap_b32_e32 v162, v156
	v_permlane16_swap_b32_e32 v163, v157
	v_fma_f32 v161, v164, v161, v165
	v_fma_f32 v163, v162, v157, v163
	v_mul_f32_e32 v160, v160, v164
	v_mul_f32_e32 v162, v162, v156
	v_mov_b32_e32 v164, v160
	v_mov_b32_e32 v165, v161
	v_mov_b32_e32 v156, v162
	v_mov_b32_e32 v157, v163
	v_permlane32_swap_b32_e32 v160, v164
	v_permlane32_swap_b32_e32 v161, v165
	v_permlane32_swap_b32_e32 v162, v156
	v_permlane32_swap_b32_e32 v163, v157
	v_fma_f32 v161, v164, v161, v165
	v_fma_f32 v163, v162, v157, v163
	v_mul_f32_e32 v160, v160, v164
	v_mul_f32_e32 v162, v162, v156
	v_fma_f32 v183, v160, v183, v161
	v_fma_f32 v207, v206, v163, v207
	v_mul_f32_e32 v182, v182, v160
	v_mul_f32_e32 v206, v206, v162
	s_waitcnt lgkmcnt(0)
; template <int PASS>
; __device__ __forceinline__ void rglru_phase(const Ctx& F, int l, const bf16_t* XRb, bf16_t* GRb, bool latent_only = false) {
;     ...
;                 for (int r = 0; r < 4; ++r) { const int tok = mt * 16 + 4 * l4 + r;
;                     const float xv = bf2f(XT[tok * XT_LD + cw + l15]);
; #pragma unroll
;                     for (int d = 0; d < 2; ++d) {
;                         const float e1 = 1.0f + __builtin_amdgcn_exp2f(ag[2 * d][r]), e2 = 1.0f + __builtin_amdgcn_exp2f(ag[2 * d + 1][r]);
;                         const float inv = __builtin_amdgcn_rcpf(e1 * e2); const float rgate = e2 * inv, igate = e1 * inv;
;                         const float a = __builtin_amdgcn_exp2f(rgate * cl2[d]);
;                         const float om = fmaf(-a, a, 1.0f);
;                         const float bv = __builtin_amdgcn_sqrtf(om) * (igate * xv);
;                         ea[d][r] = a; eb[d][r] = bv; } }
;                 if (PASS == 1) {
; #pragma unroll
;                     for (int d = 0; d < 2; ++d) {
;                         float A, B;
;                         if (d == 0) { A = ea[0][0]; B = eb[0][0];
; #pragma unroll
;                             for (int r = 1; r < 4; ++r) { B = ea[0][r] * B + eb[0][r]; A *= ea[0][r]; } }
;                         else { A = ea[1][3]; B = eb[1][3];
; #pragma unroll
;                             for (int r = 2; r >= 0; --r) { B = ea[1][r] * B + eb[1][r]; A *= ea[1][r]; } }
;                         { const float Ap = __uint_as_float(__builtin_amdgcn_ds_bpermute((lane ^ 16) << 2, __float_as_uint(A))), Bp = __uint_as_float(__builtin_amdgcn_ds_bpermute((lane ^ 16) << 2, __float_as_uint(B)));
;                           const bool mefirst = d == 0 ? ((l4 & 1) == 0) : ((l4 & 1) == 1);
;                           const float nB = mefirst ? Ap * B + Bp : A * Bp + B; A = A * Ap; B = nB; }
;                         { const float Ap = __uint_as_float(__builtin_amdgcn_ds_bpermute((lane ^ 32) << 2, __float_as_uint(A))), Bp = __uint_as_float(__builtin_amdgcn_ds_bpermute((lane ^ 32) << 2, __float_as_uint(B)));
;                           const bool mefirst = d == 0 ? (l4 < 2) : (l4 >= 2);
;                           const float nB = mefirst ? Ap * B + Bp : A * Bp + B; A = A * Ap; B = nB; }
;                         if (d == 0) { aggB[0] = A * aggB[0] + B; aggA[0] *= A; }
	v_lshlrev_b32_e32 v240, 16, v240
	v_lshlrev_b32_e32 v241, 16, v241
	v_lshlrev_b32_e32 v250, 16, v250
	v_lshlrev_b32_e32 v251, 16, v251
	v_exp_f32_e32 v184, v184
	v_exp_f32_e32 v186, v186
	v_exp_f32_e32 v192, v192
	v_exp_f32_e32 v194, v194
	v_exp_f32_e32 v185, v185
	v_exp_f32_e32 v187, v187
	v_exp_f32_e32 v193, v193
	v_pk_add_f32 v[184:185], v[184:185], 1.0 op_sel_hi:[1,0]
	v_pk_add_f32 v[186:187], v[186:187], 1.0 op_sel_hi:[1,0]
	v_exp_f32_e32 v196, v196
	v_pk_add_f32 v[192:193], v[192:193], 1.0 op_sel_hi:[1,0]
	v_exp_f32_e32 v195, v195
	v_exp_f32_e32 v188, v188
	v_exp_f32_e32 v190, v190
	v_pk_add_f32 v[194:195], v[194:195], 1.0 op_sel_hi:[1,0]
	v_exp_f32_e32 v189, v189
	v_exp_f32_e32 v191, v191
	v_exp_f32_e32 v197, v197
	v_exp_f32_e32 v198, v198
	v_pk_add_f32 v[188:189], v[188:189], 1.0 op_sel_hi:[1,0]
	v_pk_add_f32 v[190:191], v[190:191], 1.0 op_sel_hi:[1,0]
	v_exp_f32_e32 v199, v199
	v_pk_mul_f32 v[228:229], v[184:185], v[188:189]
	v_pk_mul_f32 v[230:231], v[186:187], v[190:191]
	v_pk_add_f32 v[196:197], v[196:197], 1.0 op_sel_hi:[1,0]
	v_pk_add_f32 v[198:199], v[198:199], 1.0 op_sel_hi:[1,0]
	v_rcp_f32_e32 v228, v228
	v_rcp_f32_e32 v230, v230
	v_pk_mul_f32 v[232:233], v[192:193], v[196:197]
	v_pk_mul_f32 v[234:235], v[194:195], v[198:199]
	v_rcp_f32_e32 v229, v229
	v_rcp_f32_e32 v231, v231
	v_rcp_f32_e32 v232, v232
	v_rcp_f32_e32 v234, v234
	v_pk_mul_f32 v[188:189], v[188:189], v[228:229]
	v_pk_mul_f32 v[190:191], v[190:191], v[230:231]
	v_rcp_f32_e32 v233, v233
	v_pk_mul_f32 v[188:189], v[188:189], v[180:181] op_sel_hi:[1,0]
	v_pk_mul_f32 v[190:191], v[190:191], v[180:181] op_sel_hi:[1,0]
	v_rcp_f32_e32 v235, v235
	v_pk_mul_f32 v[184:185], v[184:185], v[228:229]
	v_pk_mul_f32 v[186:187], v[186:187], v[230:231]
	v_exp_f32_e32 v188, v188
	v_pk_mul_f32 v[196:197], v[196:197], v[232:233]
	v_pk_mul_f32 v[198:199], v[198:199], v[234:235]
	v_exp_f32_e32 v189, v189
	v_pk_mul_f32 v[186:187], v[186:187], v[250:251]
	v_pk_mul_f32 v[196:197], v[196:197], v[248:249] op_sel_hi:[1,0]
	v_exp_f32_e32 v190, v190
	v_pk_mul_f32 v[192:193], v[192:193], v[232:233]
	v_pk_mul_f32 v[198:199], v[198:199], v[248:249] op_sel_hi:[1,0]
	v_exp_f32_e32 v191, v191
	v_pk_mul_f32 v[192:193], v[192:193], v[240:241]
	v_pk_mul_f32 v[194:195], v[194:195], v[234:235]
	v_exp_f32_e32 v196, v196
	v_pk_mul_f32 v[184:185], v[184:185], v[240:241]
	v_pk_fma_f32 v[230:231], v[190:191], v[190:191], 1.0 op_sel_hi:[1,1,0] neg_lo:[1,0,0] neg_hi:[1,0,0]
	v_exp_f32_e32 v197, v197
	v_pk_mul_f32 v[194:195], v[194:195], v[250:251]
	v_pk_fma_f32 v[228:229], v[188:189], v[188:189], 1.0 op_sel_hi:[1,1,0] neg_lo:[1,0,0] neg_hi:[1,0,0]
	v_sqrt_f32_e32 v230, v230
	v_pk_fma_f32 v[232:233], v[196:197], v[196:197], 1.0 op_sel_hi:[1,1,0] neg_lo:[1,0,0] neg_hi:[1,0,0]
	v_exp_f32_e32 v198, v198
	v_sqrt_f32_e32 v228, v228
	v_sqrt_f32_e32 v231, v231
	v_sqrt_f32_e32 v232, v232
	v_exp_f32_e32 v199, v199
	v_pk_mul_f32 v[186:187], v[230:231], v[186:187]
	v_sqrt_f32_e32 v233, v233
	v_sqrt_f32_e32 v229, v229
	v_pk_fma_f32 v[234:235], v[198:199], v[198:199], 1.0 op_sel_hi:[1,1,0] neg_lo:[1,0,0] neg_hi:[1,0,0]
	v_pk_mul_f32 v[192:193], v[232:233], v[192:193]
	v_pk_mul_f32 v[184:185], v[228:229], v[184:185]
	v_sqrt_f32_e32 v234, v234
	v_sqrt_f32_e32 v235, v235
	s_nop 0
	s_nop 0
	v_pk_mul_f32 v[194:195], v[234:235], v[194:195]
	v_mov_b32_e32 v161, v184
	v_mov_b32_e32 v163, v195
	v_mov_b32_e32 v160, v188
	v_mov_b32_e32 v162, v199
	v_fma_f32 v161, v189, v161, v185
	v_fma_f32 v163, v198, v163, v194
	v_mul_f32_e32 v160, v160, v189
	v_mul_f32_e32 v162, v162, v198
	v_fma_f32 v161, v190, v161, v186
	v_fma_f32 v163, v197, v163, v193
	v_mul_f32_e32 v160, v160, v190
	v_mul_f32_e32 v162, v162, v197
	v_fma_f32 v161, v191, v161, v187
	v_fma_f32 v163, v196, v163, v192
	v_mul_f32_e32 v160, v160, v191
	v_mul_f32_e32 v162, v162, v196
	v_mov_b32_e32 v164, v160
	v_mov_b32_e32 v165, v161
	v_mov_b32_e32 v156, v162
	v_mov_b32_e32 v157, v163
	v_permlane16_swap_b32_e32 v160, v164
	v_permlane16_swap_b32_e32 v161, v165
	v_permlane16_swap_b32_e32 v162, v156
	v_permlane16_swap_b32_e32 v163, v157
	v_fma_f32 v161, v164, v161, v165
	v_fma_f32 v163, v162, v157, v163
	v_mul_f32_e32 v160, v160, v164
	v_mul_f32_e32 v162, v162, v156
	v_mov_b32_e32 v164, v160
	v_mov_b32_e32 v165, v161
	v_mov_b32_e32 v156, v162
	v_mov_b32_e32 v157, v163
	v_permlane32_swap_b32_e32 v160, v164
	v_permlane32_swap_b32_e32 v161, v165
	v_permlane32_swap_b32_e32 v162, v156
	v_permlane32_swap_b32_e32 v163, v157
	v_fma_f32 v161, v164, v161, v165
	v_fma_f32 v163, v162, v157, v163
	v_mul_f32_e32 v160, v160, v164
	v_mul_f32_e32 v162, v162, v156
	v_fma_f32 v183, v160, v183, v161
	v_fma_f32 v207, v206, v163, v207
	v_mul_f32_e32 v182, v182, v160
	v_mul_f32_e32 v206, v206, v162
	s_and_saveexec_b64 s[18:19], s[46:47]
	v_add_co_u32_e32 v34, vcc, 0xfff78000, v142
	s_nop 1
	v_addc_co_u32_e32 v35, vcc, -1, v143, vcc
	global_store_dwordx2 v[34:35], v[182:183], off
	global_store_dwordx2 v[142:143], v[206:207], off
	s_branch .LBB0_559
